# NA bias + mLSTM dv branch-free + norm1 ctx partial-slab loads pipelined (16 in flight)
# speedup vs baseline: 1.0045x; 1.0045x over previous
; __device__ void norm_phase(const Params& p, int layer, int which, int nrows, char* smem) {
;     ...
;     for (int i = 0; i < 4; ++i) {
;       v[0][i] = *(const f32x4*)(src + i * 256 + lane * 4);
;       v[1][i] = *(const f32x4*)(src + DM + i * 256 + lane * 4);
;     }
;     if (which == 0 && layer == 1 && !latent) {
;       const float* pb = (const float*)p.obuf + (size_t)(row0 - NLAT) * DM;
; #pragma unroll
;       for (int q = 0; q < 4; ++q)
; #pragma unroll
;         for (int i = 0; i < 4; ++i) {
;           v[0][i] += *(const f32x4*)(pb + (size_t)q * (NBATCH * CTXL) * DM + i * 256 + lane * 4);
;           v[1][i] += *(const f32x4*)(pb + (size_t)q * (NBATCH * CTXL) * DM + DM + i * 256 + lane * 4);
;         }
;     }
.LBB0_87:
	v_lshlrev_b64 v[4:5], 12, v[4:5]
	s_waitcnt lgkmcnt(0)
	v_lshl_add_u64 v[2:3], v[2:3], 0, v[4:5]
	v_lshlrev_b32_e32 v0, 2, v34
	v_lshl_add_u64 v[2:3], v[2:3], 0, v[0:1]
	v_add_co_u32_e32 v26, vcc, 0x1000, v2
	v_lshl_add_u64 v[30:31], v[2:3], 0, s[26:27]
	s_nop 0
	v_addc_co_u32_e32 v27, vcc, 0, v3, vcc
	global_load_dwordx4 v[22:25], v[2:3], off
	global_load_dwordx4 v[14:17], v[2:3], off offset:1024
	global_load_dwordx4 v[18:21], v[30:31], off offset:1024
	global_load_dwordx4 v[6:9], v[30:31], off offset:2048
	global_load_dwordx4 v[10:13], v[2:3], off offset:2048
	s_nop 0
	global_load_dwordx4 v[2:5], v[2:3], off offset:3072
	s_nop 0
	global_load_dwordx4 v[26:29], v[26:27], off
	s_nop 0
	global_load_dwordx4 v[30:33], v[30:31], off offset:3072
	v_readlane_b32 s6, v254, 32
	v_readlane_b32 s7, v254, 33
	s_nor_b64 s[8:9], s[6:7], s[44:45]
	s_and_saveexec_b64 s[6:7], s[8:9]
	s_cbranch_execz .LBB0_89
	v_add_u32_e32 v52, 0xffff8000, v44
	v_mov_b32_e32 v53, v1
	v_lshlrev_b64 v[52:53], 12, v[52:53]
	v_lshl_add_u64 v[52:53], s[82:83], 0, v[52:53]
	v_lshl_add_u64 v[52:53], v[52:53], 0, v[0:1]
	s_mov_b64 s[8:9], 0x1000
	v_lshl_add_u64 v[134:135], v[52:53], 0, s[8:9]
	s_mov_b64 s[8:9], 0x1000000
	v_lshl_add_u64 v[136:137], v[52:53], 0, s[8:9]
	v_lshl_add_u64 v[138:139], v[134:135], 0, s[8:9]
	v_lshl_add_u64 v[140:141], v[136:137], 0, s[8:9]
	v_lshl_add_u64 v[142:143], v[138:139], 0, s[8:9]
	v_lshl_add_u64 v[144:145], v[140:141], 0, s[8:9]
	v_lshl_add_u64 v[146:147], v[142:143], 0, s[8:9]
	global_load_dwordx4 v[148:151], v[52:53], off
	global_load_dwordx4 v[152:155], v[52:53], off offset:1024
	global_load_dwordx4 v[156:159], v[52:53], off offset:2048
	global_load_dwordx4 v[160:163], v[52:53], off offset:3072
	global_load_dwordx4 v[164:167], v[134:135], off
	global_load_dwordx4 v[168:171], v[134:135], off offset:1024
	global_load_dwordx4 v[178:181], v[134:135], off offset:2048
	global_load_dwordx4 v[182:185], v[134:135], off offset:3072
	global_load_dwordx4 v[186:189], v[136:137], off
	global_load_dwordx4 v[190:193], v[136:137], off offset:1024
	global_load_dwordx4 v[194:197], v[136:137], off offset:2048
	global_load_dwordx4 v[198:201], v[136:137], off offset:3072
	global_load_dwordx4 v[202:205], v[138:139], off
	global_load_dwordx4 v[206:209], v[138:139], off offset:1024
	global_load_dwordx4 v[210:213], v[138:139], off offset:2048
	global_load_dwordx4 v[214:217], v[138:139], off offset:3072
	s_waitcnt vmcnt(8)
	v_pk_add_f32 v[22:23], v[22:23], v[148:149]
	v_pk_add_f32 v[24:25], v[24:25], v[150:151]
	v_pk_add_f32 v[14:15], v[14:15], v[152:153]
	v_pk_add_f32 v[16:17], v[16:17], v[154:155]
	v_pk_add_f32 v[10:11], v[10:11], v[156:157]
	v_pk_add_f32 v[12:13], v[12:13], v[158:159]
	v_pk_add_f32 v[2:3], v[2:3], v[160:161]
	v_pk_add_f32 v[4:5], v[4:5], v[162:163]
	v_pk_add_f32 v[26:27], v[26:27], v[164:165]
	v_pk_add_f32 v[28:29], v[28:29], v[166:167]
	v_pk_add_f32 v[18:19], v[18:19], v[168:169]
	v_pk_add_f32 v[20:21], v[20:21], v[170:171]
	v_pk_add_f32 v[6:7], v[6:7], v[178:179]
	v_pk_add_f32 v[8:9], v[8:9], v[180:181]
	v_pk_add_f32 v[30:31], v[30:31], v[182:183]
	v_pk_add_f32 v[32:33], v[32:33], v[184:185]
	global_load_dwordx4 v[148:151], v[140:141], off
	global_load_dwordx4 v[152:155], v[140:141], off offset:1024
	global_load_dwordx4 v[156:159], v[140:141], off offset:2048
	global_load_dwordx4 v[160:163], v[140:141], off offset:3072
	global_load_dwordx4 v[164:167], v[142:143], off
	global_load_dwordx4 v[168:171], v[142:143], off offset:1024
	global_load_dwordx4 v[178:181], v[142:143], off offset:2048
	global_load_dwordx4 v[182:185], v[142:143], off offset:3072
	s_waitcnt vmcnt(8)
	v_pk_add_f32 v[22:23], v[22:23], v[186:187]
	v_pk_add_f32 v[24:25], v[24:25], v[188:189]
	v_pk_add_f32 v[14:15], v[14:15], v[190:191]
	v_pk_add_f32 v[16:17], v[16:17], v[192:193]
	v_pk_add_f32 v[10:11], v[10:11], v[194:195]
	v_pk_add_f32 v[12:13], v[12:13], v[196:197]
	v_pk_add_f32 v[2:3], v[2:3], v[198:199]
	v_pk_add_f32 v[4:5], v[4:5], v[200:201]
	v_pk_add_f32 v[26:27], v[26:27], v[202:203]
	v_pk_add_f32 v[28:29], v[28:29], v[204:205]
	v_pk_add_f32 v[18:19], v[18:19], v[206:207]
	v_pk_add_f32 v[20:21], v[20:21], v[208:209]
	v_pk_add_f32 v[6:7], v[6:7], v[210:211]
	v_pk_add_f32 v[8:9], v[8:9], v[212:213]
	v_pk_add_f32 v[30:31], v[30:31], v[214:215]
	v_pk_add_f32 v[32:33], v[32:33], v[216:217]
	global_load_dwordx4 v[186:189], v[144:145], off
	global_load_dwordx4 v[190:193], v[144:145], off offset:1024
	global_load_dwordx4 v[194:197], v[144:145], off offset:2048
	global_load_dwordx4 v[198:201], v[144:145], off offset:3072
	global_load_dwordx4 v[202:205], v[146:147], off
	global_load_dwordx4 v[206:209], v[146:147], off offset:1024
	global_load_dwordx4 v[210:213], v[146:147], off offset:2048
	global_load_dwordx4 v[214:217], v[146:147], off offset:3072
	s_waitcnt vmcnt(8)
	v_pk_add_f32 v[22:23], v[22:23], v[148:149]
	v_pk_add_f32 v[24:25], v[24:25], v[150:151]
	v_pk_add_f32 v[14:15], v[14:15], v[152:153]
	v_pk_add_f32 v[16:17], v[16:17], v[154:155]
	v_pk_add_f32 v[10:11], v[10:11], v[156:157]
	v_pk_add_f32 v[12:13], v[12:13], v[158:159]
	v_pk_add_f32 v[2:3], v[2:3], v[160:161]
	v_pk_add_f32 v[4:5], v[4:5], v[162:163]
	v_pk_add_f32 v[26:27], v[26:27], v[164:165]
	v_pk_add_f32 v[28:29], v[28:29], v[166:167]
	v_pk_add_f32 v[18:19], v[18:19], v[168:169]
	v_pk_add_f32 v[20:21], v[20:21], v[170:171]
	v_pk_add_f32 v[6:7], v[6:7], v[178:179]
	v_pk_add_f32 v[8:9], v[8:9], v[180:181]
	v_pk_add_f32 v[30:31], v[30:31], v[182:183]
	v_pk_add_f32 v[32:33], v[32:33], v[184:185]
	s_waitcnt vmcnt(0)
	v_pk_add_f32 v[22:23], v[22:23], v[186:187]
	v_pk_add_f32 v[24:25], v[24:25], v[188:189]
	v_pk_add_f32 v[14:15], v[14:15], v[190:191]
	v_pk_add_f32 v[16:17], v[16:17], v[192:193]
	v_pk_add_f32 v[10:11], v[10:11], v[194:195]
	v_pk_add_f32 v[12:13], v[12:13], v[196:197]
	v_pk_add_f32 v[2:3], v[2:3], v[198:199]
	v_pk_add_f32 v[4:5], v[4:5], v[200:201]
	v_pk_add_f32 v[26:27], v[26:27], v[202:203]
	v_pk_add_f32 v[28:29], v[28:29], v[204:205]
	v_pk_add_f32 v[18:19], v[18:19], v[206:207]
	v_pk_add_f32 v[20:21], v[20:21], v[208:209]
	v_pk_add_f32 v[6:7], v[6:7], v[210:211]
	v_pk_add_f32 v[8:9], v[8:9], v[212:213]
	v_pk_add_f32 v[30:31], v[30:31], v[214:215]
	v_pk_add_f32 v[32:33], v[32:33], v[216:217]
